# GLA chunk-state pass and SWA pass: every other workgroup of an XCD runs them in the opposite order so memory-bound and compute-bound work overlap
# speedup vs baseline: 1.0407x; 1.0027x over previous
.LBB0_416:
	s_or_b64 exec, exec, s[6:7]
	v_readlane_b32 s8, v254, 7
	v_readlane_b32 s9, v254, 8
	s_mov_b64 s[6:7], s[84:85]
	v_mov_b32_e32 v21, v208
	s_and_b64 vcc, exec, s[8:9]
	s_waitcnt lgkmcnt(0)
	s_barrier
	s_mov_b32 s98, 0
	s_bitcmp1_b32 s78, 3
	s_cbranch_scc0 .Lswap_ga_entry
	s_mov_b32 s98, 1
	s_branch .LBB0_423
.Lswap_ga_entry:
	s_cbranch_vccz .Lswap_ga_exit
	s_load_dwordx2 s[6:7], s[6:7], 0x80
	v_ashrrev_i32_e32 v3, 8, v21
	v_lshlrev_b32_e32 v0, 1, v21
	v_and_b32_e32 v20, 62, v0
	v_add_u32_e32 v0, s94, v3
	v_bfe_u32 v31, v0, 7, 2
	v_lshlrev_b32_e32 v1, 4, v0
	v_lshlrev_b32_e32 v0, 6, v0
	v_bfe_u32 v30, v21, 5, 3
	v_and_b32_e32 v0, 0x1fc0, v0
	s_movk_i32 s10, 0xe000
	s_waitcnt lgkmcnt(0)
	s_add_u32 s18, s6, 0xbe00000
	v_and_or_b32 v32, v1, s10, v0
	v_lshlrev_b32_e32 v54, 3, v30
	s_addc_u32 s19, s7, 0
	v_or_b32_e32 v0, v32, v54
	s_add_u32 s8, s6, 0x14e00000
	v_or_b32_e32 v18, 2, v0
	s_addc_u32 s9, s7, 0
	v_lshlrev_b32_e32 v4, 7, v31
	v_mov_b32_e32 v5, v2
	v_mov_b64_e32 v[12:13], s[18:19]
	v_or_b32_e32 v14, 1, v0
	v_ashrrev_i32_e32 v19, 31, v18
	v_or_b32_e32 v26, 3, v0
	v_lshl_add_u64 v[6:7], s[8:9], 0, v[4:5]
	v_lshlrev_b32_e32 v22, 1, v20
	v_mov_b32_e32 v23, v2
	v_ashrrev_i32_e32 v1, 31, v0
	v_ashrrev_i32_e32 v15, 31, v14
	v_lshlrev_b64 v[24:25], 9, v[18:19]
	v_mad_i64_i32 v[18:19], s[10:11], v18, s62, v[12:13]
	v_ashrrev_i32_e32 v27, 31, v26
	v_lshl_add_u64 v[6:7], v[6:7], 0, v[22:23]
	v_lshlrev_b64 v[8:9], 9, v[0:1]
	v_mad_i64_i32 v[10:11], s[10:11], v0, s62, v[12:13]
	v_lshlrev_b64 v[16:17], 9, v[14:15]
	v_mad_i64_i32 v[14:15], s[10:11], v14, s62, v[12:13]
	v_lshl_add_u64 v[18:19], v[18:19], 0, v[4:5]
	v_lshlrev_b64 v[28:29], 9, v[26:27]
	v_mad_i64_i32 v[26:27], s[10:11], v26, s62, v[12:13]
	v_lshl_add_u64 v[8:9], v[6:7], 0, v[8:9]
	v_lshl_add_u64 v[10:11], v[10:11], 0, v[4:5]
	v_lshl_add_u64 v[14:15], v[14:15], 0, v[4:5]
	v_lshl_add_u64 v[18:19], v[18:19], 0, v[22:23]
	v_lshl_add_u64 v[28:29], v[6:7], 0, v[28:29]
	v_lshl_add_u64 v[26:27], v[26:27], 0, v[4:5]
	v_lshl_add_u64 v[10:11], v[10:11], 0, v[22:23]
	v_lshl_add_u64 v[16:17], v[6:7], 0, v[16:17]
	v_lshl_add_u64 v[14:15], v[14:15], 0, v[22:23]
	v_lshl_add_u64 v[24:25], v[6:7], 0, v[24:25]
	v_lshl_add_u64 v[26:27], v[26:27], 0, v[22:23]
	global_load_dword v34, v[8:9], off
	global_load_dword v55, v[10:11], off offset:512
	global_load_dword v35, v[16:17], off
	global_load_dword v56, v[14:15], off offset:512
	global_load_dword v41, v[24:25], off
	global_load_dword v57, v[18:19], off offset:512
	s_nop 0
	global_load_dword v28, v[28:29], off
	s_nop 0
	global_load_dword v58, v[26:27], off offset:512
	v_or_b32_e32 v8, 4, v0
	v_or_b32_e32 v18, 6, v0
	v_ashrrev_i32_e32 v9, 31, v8
	v_or_b32_e32 v14, 5, v0
	v_ashrrev_i32_e32 v19, 31, v18
	v_lshlrev_b64 v[10:11], 9, v[8:9]
	v_ashrrev_i32_e32 v15, 31, v14
	v_lshlrev_b64 v[24:25], 9, v[18:19]
	v_or_b32_e32 v0, 7, v0
	v_lshl_add_u64 v[10:11], v[6:7], 0, v[10:11]
	v_lshlrev_b64 v[16:17], 9, v[14:15]
	v_lshl_add_u64 v[24:25], v[6:7], 0, v[24:25]
	v_ashrrev_i32_e32 v1, 31, v0
	v_lshl_add_u64 v[16:17], v[6:7], 0, v[16:17]
	global_load_dword v26, v[10:11], off
	global_load_dword v27, v[16:17], off
	s_nop 0
	global_load_dword v25, v[24:25], off
	v_lshlrev_b64 v[10:11], 9, v[0:1]
	v_mad_i64_i32 v[8:9], s[10:11], v8, s62, v[12:13]
	v_lshl_add_u64 v[6:7], v[6:7], 0, v[10:11]
	v_mad_i64_i32 v[0:1], s[10:11], v0, s62, v[12:13]
	global_load_dword v29, v[6:7], off
	v_lshl_add_u64 v[6:7], v[8:9], 0, v[4:5]
	v_mad_i64_i32 v[8:9], s[10:11], v14, s62, v[12:13]
	v_mad_i64_i32 v[10:11], s[10:11], v18, s62, v[12:13]
	v_lshl_add_u64 v[0:1], v[0:1], 0, v[4:5]
	v_lshl_add_u64 v[8:9], v[8:9], 0, v[4:5]
	v_lshl_add_u64 v[10:11], v[10:11], 0, v[4:5]
	v_lshl_add_u64 v[0:1], v[0:1], 0, v[22:23]
	v_lshl_add_u64 v[6:7], v[6:7], 0, v[22:23]
	v_lshl_add_u64 v[8:9], v[8:9], 0, v[22:23]
	v_lshl_add_u64 v[10:11], v[10:11], 0, v[22:23]
	global_load_dword v71, v[0:1], off offset:512
	global_load_dword v70, v[10:11], off offset:512
	global_load_dword v69, v[8:9], off offset:512
	global_load_dword v33, v[6:7], off offset:512
	v_lshlrev_b32_e32 v0, 3, v21
	v_and_b32_e32 v24, 0x78, v0
	v_lshrrev_b32_e32 v0, 3, v21
	v_and_b32_e32 v59, 30, v0
	v_or_b32_e32 v18, v32, v59
	v_or_b32_e32 v4, 1, v18
	v_mad_i64_i32 v[0:1], s[10:11], v18, s62, v[12:13]
	v_lshlrev_b32_e32 v14, 8, v31
	v_mov_b32_e32 v15, v2
	v_mad_i64_i32 v[4:5], s[10:11], v4, s62, v[12:13]
	v_lshl_add_u64 v[0:1], v[0:1], 0, v[14:15]
	v_lshlrev_b32_e32 v16, 1, v24
	v_mov_b32_e32 v17, v2
	v_lshl_add_u64 v[4:5], v[4:5], 0, v[14:15]
	v_lshl_add_u64 v[0:1], v[0:1], 0, v[16:17]
	v_lshl_add_u64 v[8:9], v[4:5], 0, v[16:17]
	global_load_dwordx4 v[4:7], v[0:1], off offset:1024
	s_nop 0
	global_load_dwordx4 v[8:11], v[8:9], off offset:1024
	v_or_b32_e32 v0, 32, v18
	v_or_b32_e32 v18, 33, v18
	v_mad_i64_i32 v[0:1], s[10:11], v0, s62, v[12:13]
	v_mad_i64_i32 v[12:13], s[10:11], v18, s62, v[12:13]
	v_lshl_add_u64 v[0:1], v[0:1], 0, v[14:15]
	v_lshl_add_u64 v[12:13], v[12:13], 0, v[14:15]
	v_lshl_add_u64 v[0:1], v[0:1], 0, v[16:17]
	v_lshl_add_u64 v[16:17], v[12:13], 0, v[16:17]
	global_load_dwordx4 v[12:15], v[0:1], off offset:1024
	s_nop 0
	global_load_dwordx4 v[16:19], v[16:17], off offset:1024
	s_mov_b32 s10, 0xa000
	v_mad_i32_i24 v31, v3, s10, 0
	v_mul_u32_u24_e32 v1, 0x90, v20
	v_lshlrev_b32_e32 v0, 2, v20
	v_add_u32_e32 v60, v31, v0
	s_mov_b64 s[10:11], 0x3d00000
	s_movk_i32 s12, 0x9f
	s_waitcnt vmcnt(19)
	v_lshlrev_b32_e32 v36, 16, v34
	v_and_b32_e32 v37, 0xffff0000, v34
	v_and_b32_e32 v34, 15, v21
	s_waitcnt vmcnt(17)
	v_lshlrev_b32_e32 v38, 16, v35
	v_and_b32_e32 v39, 0xffff0000, v35
	s_movk_i32 s14, 0xbf
	s_waitcnt vmcnt(13)
	v_lshlrev_b32_e32 v42, 16, v28
	v_and_b32_e32 v43, 0xffff0000, v28
	v_cmp_lt_u32_sdwa s[20:21], v21, v213 src0_sel:BYTE_0 src1_sel:DWORD
	v_mul_u32_u24_e32 v32, 0x90, v24
	v_cmp_gt_u32_sdwa s[12:13], v21, s12 src0_sel:BYTE_0 src1_sel:DWORD
	v_cmp_gt_u32_sdwa s[14:15], v21, s14 src0_sel:BYTE_0 src1_sel:DWORD
	s_mov_b64 s[22:23], 0x16e00000
	v_cmp_eq_u32_e64 s[16:17], 7, v30
	v_lshlrev_b32_e32 v40, 16, v41
	v_and_b32_e32 v41, 0xffff0000, v41
	v_or_b32_e32 v63, 32, v59
	s_mov_b32 s24, s78
	s_waitcnt vmcnt(11)
	v_lshlrev_b32_e32 v44, 16, v26
	v_and_b32_e32 v45, 0xffff0000, v26
	v_lshlrev_b32_e32 v26, 4, v30
	v_add3_u32 v61, v31, v1, v26
	v_mov_b32_e32 v1, v2
	v_bfe_u32 v26, v21, 4, 2
	s_waitcnt vmcnt(10)
	v_lshlrev_b32_e32 v46, 16, v27
	v_and_b32_e32 v47, 0xffff0000, v27
	v_lshl_add_u64 v[0:1], s[6:7], 0, v[0:1]
	s_waitcnt vmcnt(8)
	v_lshlrev_b32_e32 v50, 16, v29
	v_and_b32_e32 v51, 0xffff0000, v29
	v_lshl_add_u64 v[28:29], s[8:9], 0, v[22:23]
	v_lshrrev_b32_e32 v22, 2, v21
	v_and_b32_e32 v22, 48, v22
	v_or_b32_e32 v23, v22, v34
	s_movk_i32 s8, 0x90
	v_mad_u32_u24 v35, v23, s8, v31
	v_lshlrev_b32_e32 v22, 1, v22
	v_mov_b32_e32 v23, v2
	v_lshlrev_b32_e32 v52, 4, v26
	v_lshl_add_u64 v[22:23], s[6:7], 0, v[22:23]
	v_lshlrev_b32_e32 v26, 3, v26
	v_mov_b32_e32 v27, v2
	v_lshl_add_u64 v[0:1], v[0:1], 0, s[10:11]
	v_lshl_add_u64 v[22:23], v[22:23], 0, v[26:27]
	s_movk_i32 s8, 0x5f
	s_movk_i32 s10, 0x7f
	v_lshlrev_b32_e32 v26, 7, v34
	v_cmp_gt_u32_sdwa s[6:7], v21, v214 src0_sel:BYTE_0 src1_sel:DWORD
	v_cmp_gt_u32_sdwa s[8:9], v21, s8 src0_sel:BYTE_0 src1_sel:DWORD
	v_cmp_gt_u32_sdwa s[10:11], v21, s10 src0_sel:BYTE_0 src1_sel:DWORD
	v_lshlrev_b32_e32 v21, 1, v59
	v_lshl_add_u64 v[22:23], v[22:23], 0, v[26:27]
	v_lshlrev_b32_e32 v48, 16, v25
	v_and_b32_e32 v49, 0xffff0000, v25
	v_lshlrev_b32_e32 v25, 8, v30
	v_add_u32_e32 v53, v31, v52
	v_add3_u32 v62, v31, v32, v21
	v_lshl_add_u64 v[30:31], v[22:23], 0, s[22:23]
	v_readlane_b32 s22, v254, 39
	v_mul_u32_u24_e32 v21, 0x90, v34
	v_add_u32_e32 v66, v60, v25
	v_lshl_add_u32 v64, v3, 6, s22
	v_readlane_b32 s22, v254, 41
	v_lshlrev_b32_e32 v32, 1, v20
	v_lshlrev_b32_e32 v34, 1, v24
	v_lshl_add_u32 v65, v3, 4, s22
	v_add_u32_e32 v67, v35, v52
	v_add_u32_e32 v68, v53, v21
	s_branch .LBB0_419

.Lswap_ga_exit:
	s_cmp_eq_u32 s98, 2
	s_cbranch_scc1 .LBB0_433

.Lswap_swa_exit:
	s_cmp_lg_u32 s98, 1
	s_cbranch_scc1 .LBB0_433
	s_mov_b32 s98, 2
	v_readlane_b32 s8, v254, 7
	v_readlane_b32 s9, v254, 8
	s_mov_b64 s[6:7], s[84:85]
	v_mov_b32_e32 v21, v208
	s_and_b64 vcc, exec, s[8:9]
	s_branch .Lswap_ga_entry

	.amdhsa_kernel _Z9hymba_fwd4Args
		.amdhsa_group_segment_fixed_size 0
		.amdhsa_private_segment_fixed_size 0
		.amdhsa_kernarg_size 392
		.amdhsa_user_sgpr_count 2
		.amdhsa_user_sgpr_dispatch_ptr 0
		.amdhsa_user_sgpr_queue_ptr 0
		.amdhsa_user_sgpr_kernarg_segment_ptr 1
		.amdhsa_user_sgpr_dispatch_id 0
		.amdhsa_user_sgpr_kernarg_preload_length 0
		.amdhsa_user_sgpr_kernarg_preload_offset 0
		.amdhsa_user_sgpr_private_segment_size 0
		.amdhsa_uses_dynamic_stack 0
		.amdhsa_enable_private_segment 0
		.amdhsa_system_sgpr_workgroup_id_x 1
		.amdhsa_system_sgpr_workgroup_id_y 0
		.amdhsa_system_sgpr_workgroup_id_z 0
		.amdhsa_system_sgpr_workgroup_info 0
		.amdhsa_system_vgpr_workitem_id 2
		.amdhsa_next_free_vgpr 255
		.amdhsa_next_free_sgpr 99
		.amdhsa_accum_offset 256
		.amdhsa_reserve_vcc 1
		.amdhsa_float_round_mode_32 0
		.amdhsa_float_round_mode_16_64 0
		.amdhsa_float_denorm_mode_32 3
		.amdhsa_float_denorm_mode_16_64 3
		.amdhsa_dx10_clamp 1
		.amdhsa_ieee_mode 1
		.amdhsa_fp16_overflow 0
		.amdhsa_tg_split 0
		.amdhsa_exception_fp_ieee_invalid_op 0
		.amdhsa_exception_fp_denorm_src 0
		.amdhsa_exception_fp_ieee_div_zero 0
		.amdhsa_exception_fp_ieee_overflow 0
		.amdhsa_exception_fp_ieee_underflow 0
		.amdhsa_exception_fp_ieee_inexact 0
		.amdhsa_exception_int_div_zero 0
	.end_amdhsa_kernel

amdhsa.kernels:
  - .agpr_count:     0
    .args:
      - .offset:         0
        .size:           136
        .value_kind:     by_value
      - .offset:         136
        .size:           4
        .value_kind:     hidden_block_count_x
      - .offset:         140
        .size:           4
        .value_kind:     hidden_block_count_y
      - .offset:         144
        .size:           4
        .value_kind:     hidden_block_count_z
      - .offset:         148
        .size:           2
        .value_kind:     hidden_group_size_x
      - .offset:         150
        .size:           2
        .value_kind:     hidden_group_size_y
      - .offset:         152
        .size:           2
        .value_kind:     hidden_group_size_z
      - .offset:         154
        .size:           2
        .value_kind:     hidden_remainder_x
      - .offset:         156
        .size:           2
        .value_kind:     hidden_remainder_y
      - .offset:         158
        .size:           2
        .value_kind:     hidden_remainder_z
      - .offset:         176
        .size:           8
        .value_kind:     hidden_global_offset_x
      - .offset:         184
        .size:           8
        .value_kind:     hidden_global_offset_y
      - .offset:         192
        .size:           8
        .value_kind:     hidden_global_offset_z
      - .offset:         200
        .size:           2
        .value_kind:     hidden_grid_dims
      - .offset:         224
        .size:           8
        .value_kind:     hidden_multigrid_sync_arg
      - .offset:         256
        .size:           4
        .value_kind:     hidden_dynamic_lds_size
    .group_segment_fixed_size: 0
    .kernarg_segment_align: 8
    .kernarg_segment_size: 392
    .language:       OpenCL C
    .language_version:
      - 2
      - 0
    .max_flat_workgroup_size: 512
    .name:           _Z9hymba_fwd4Args
    .private_segment_fixed_size: 0
    .sgpr_count:     105
    .sgpr_spill_count: 99
    .symbol:         _Z9hymba_fwd4Args.kd
    .uniform_work_group_size: 1
    .uses_dynamic_stack: false
    .vgpr_count:     255
    .vgpr_spill_count: 0
    .wavefront_size: 64
